# P3 and P4 run without a grid barrier in between: V-transposed output moved to unused regions of out and ws
# speedup vs baseline: 1.0422x; 1.0055x over previous
; __device__ __forceinline__ void xcd_barrier(const XcdBarrier& b) {
;     asm volatile("s_waitcnt vmcnt(0)" ::: "memory");
;     __syncthreads();
;     if (threadIdx.x == 0) {
;         unsigned* bar = b.bar;
;         __builtin_amdgcn_s_waitcnt(0);
;         unsigned nloc = b.st[0], nx = b.st[1];
;         if (nloc == 0u) { xcd_barrier_complete(bar, b.x, nloc, nx); b.st[0] = nloc; b.st[1] = nx; }
.LBB0_438:
	s_branch .LBB0_492
	s_cmp_lt_i32 s85, 5
	s_cbranch_scc1 .LBB0_492
	s_waitcnt vmcnt(0)
	s_waitcnt vmcnt(0)
	s_barrier
	s_mov_b64 s[4:5], exec
	v_readlane_b32 s6, v255, 1
	v_readlane_b32 s7, v255, 2
	s_and_b64 s[6:7], s[4:5], s[6:7]
	s_mov_b64 exec, s[6:7]
	s_cbranch_execz .LBB0_491
	s_add_i32 s3, 0, 0x23fc0
	v_mov_b32_e32 v0, s3
	s_waitcnt vmcnt(0) expcnt(0) lgkmcnt(0)
	ds_read_b32 v2, v0
	s_add_i32 s3, 0, 0x23fc4
	v_mov_b32_e32 v0, s3
	ds_read_b32 v0, v0
	s_waitcnt lgkmcnt(1)
	v_cmp_ne_u32_e32 vcc, 0, v2
	s_cbranch_vccnz .LBB0_455
	s_add_u32 s6, s30, 0x80200
	s_addc_u32 s7, s31, 0
	s_add_u32 s8, s30, 0x80400
	s_addc_u32 s9, s31, 0
	s_add_u32 s10, s30, 0x80500
	s_addc_u32 s11, s31, 0
	s_add_u32 s12, s30, 0x80600
	s_addc_u32 s13, s31, 0
	s_add_u32 s14, s30, 0x80700
	s_addc_u32 s15, s31, 0
	s_add_u32 s16, s30, 0x80800
	s_addc_u32 s17, s31, 0
	s_add_u32 s18, s30, 0x80900
	s_addc_u32 s19, s31, 0
	s_add_u32 s20, s30, 0x80a00
	s_addc_u32 s21, s31, 0
	s_add_u32 s22, s30, 0x80b00
	s_addc_u32 s23, s31, 0
	s_add_u32 s24, s30, 0x80c00
	s_addc_u32 s25, s31, 0
	s_add_u32 s26, s30, 0x80d00
	s_addc_u32 s27, s31, 0
	s_add_u32 s36, s30, 0x80e00
	s_addc_u32 s37, s31, 0
	s_add_u32 s38, s30, 0x80f00
	s_addc_u32 s39, s31, 0
	s_add_u32 s42, s30, 0x81000
	s_load_dword s3, s[0:1], 0x118
	s_addc_u32 s43, s31, 0
	s_add_u32 s48, s30, 0x81100
	s_addc_u32 s49, s31, 0
	s_add_u32 s54, s30, 0x81200
	s_addc_u32 s55, s31, 0
	s_waitcnt lgkmcnt(0)
	s_mul_i32 s3, s87, s3
	s_add_u32 s58, s30, 0x81300
	s_mul_i32 s3, s3, s86
	s_addc_u32 s59, s31, 0
	s_mov_b32 s28, 1
	v_mov_b32_e32 v16, 0
	s_branch .LBB0_443

;     __host__ __device__ void init(int M, int N, int G_, int c_) { base.init(M, N, G_, c_); }
; __device__ __forceinline__ unsigned cvt_pk_bf16(float lo, float hi) { unsigned r; asm volatile("v_cvt_pk_bf16_f32 %0, %1, %2" : "=v"(r) : "v"(lo), "v"(hi)); return r; }
;     __device__ __forceinline__ void operator()(const f32x4 (&acc)[2][2][4][2], const Unit& u, int wr, int wc, int fr, int fq) const {
;     ...
;                 for (int m = 0; m < 4; ++m) { const f32x4 v0 = acc[ai][bj][m][0] * s0, v1 = acc[ai][bj][m][1] * s1;
;                     u32x4 w; w.x = cvt_pk_bf16(v0[0], v0[1]); w.y = cvt_pk_bf16(v0[2], v0[3]); w.z = cvt_pk_bf16(v1[0], v1[1]); w.w = cvt_pk_bf16(v1[2], v1[3]);
;                     *(u32x4*)(O + (size_t)(row0 + ai * HALF + m * 16) * ldc + col0 + bj * HALF) = w; }
; __global__ void __launch_bounds__(NTHR) mk_fwd(Args a) {
;     ...
;                { pg8::Gemm g{WSB(WS_WUKV + 512 * 1024), WSB(SL(5)), 512, T, 256, 512}; pg8::StaticOrder S; S.init(512, T, G, bid);
;                  pg8::EpiColScale E{WSB(SL(8)), T, (const float*)(ws + WS_RSKV), 1.f / 256.f};
;                  pg8::gemm_phase<pg8::EpiColScale, pg8::StaticOrder, true, true>(lds, g, S, E); } )
.LBB0_551:
	s_cmp_eq_u32 s6, 0
	s_cbranch_scc0 .Lvt_p1
	s_add_u32 s24, s50, 0x7000000
	s_addc_u32 s25, s51, 0
	s_branch .Lvt_pd
.Lvt_p1:
	s_add_u32 s24, s30, 0x1800000
	s_addc_u32 s25, s31, 0

; #define LAS __attribute__((address_space(3)))
; #define PHASE(k, ...) if (IN(k)) { { __VA_ARGS__ } if (DUPON(k)) { __VA_ARGS__ } SEAM(k); }
; __device__ __forceinline__ void attn_unit64(const bf16_t* Q, const bf16_t* K, const bf16_t* Vt, bf16_t* O, int bh, int qb8, float mfix, LAS unsigned char* lds) {
;     const int tid = threadIdx.x, lane = tid & 63, wid = __builtin_amdgcn_readfirstlane(tid >> 6), r = lane & 31, hh = lane >> 5;
;     LAS bf16_t* Kb = (LAS bf16_t*)lds;
;     LAS bf16_t* Vb = (LAS bf16_t*)(lds + 2 * 64 * 104 * 2);
;     const bf16_t* Qh = Q + (size_t)bh * SEQ * 96; const bf16_t* Kh = K + (size_t)bh * SEQ * 96; const bf16_t* Vh = Vt + (size_t)(bh & 7) * 64 * T + (size_t)(bh >> 3) * SEQ;
;     const int q0 = qb8 * 512, qw = q0 + wid * 64, NTL = 8 * (qb8 + 1), tmaxw = 8 * qb8 + wid;
;     LAS bf16x8* Qs = (LAS bf16x8*)(lds + 2 * 64 * 104 * 2 + 2 * 64 * 68 * 2) + tid;
; #pragma unroll
;     for (int d0 = 0; d0 < 6; ++d0) { Qs[512 * d0] = __builtin_nontemporal_load((const bf16x8*)(Qh + (size_t)(qw + r) * 96 + 16 * d0 + 8 * hh)); Qs[512 * (6 + d0)] = __builtin_nontemporal_load((const bf16x8*)(Qh + (size_t)(qw + 32 + r) * 96 + 16 * d0 + 8 * hh)); }
;     f32x16 oA0, oA1, oB0, oB1;
; #pragma unroll
;     for (int i = 0; i < 16; ++i) { oA0[i] = 0.f; oA1[i] = 0.f; oB0[i] = 0.f; oB1[i] = 0.f; }
;     float lA = 0.f, lB = 0.f;
;     const int c2 = 512 + tid, kr1 = tid / 12, kc1 = tid % 12, kr2 = c2 / 12, kc2 = c2 % 12, vr = tid >> 3, vc = tid & 7;
;     u32x4 kA, kB = {0u, 0u, 0u, 0u}, vA;
; __global__ void __launch_bounds__(NTHR) mk_fwd(Args a) {
;     ...
;     PHASE(7,  const bf16_t* Q = WSB(SL(3)); const bf16_t* K = (const bf16_t*)((unsigned char*)a.out + 64 * MiB); const bf16_t* Vt = WSB(SL(8)); bf16_t* O = (bf16_t*)a.out;
;                  float mfix; { const int ln = threadIdx.x & 63; float gqm = fmaxf(fabsf(a.in[11][ln]), fabsf(a.in[11][64 + (ln & 31)])), gkm = fmaxf(fabsf(a.in[12][ln]), fabsf(a.in[12][64 + (ln & 31)]));
;                      for (int o = 1; o < 64; o <<= 1) { gqm = fmaxf(gqm, __shfl_xor(gqm, o)); gkm = fmaxf(gkm, __shfl_xor(gkm, o)); }
;                      mfix = 14.135f * 1.02f * gqm * gkm; }
;                  const bool fix = mfix <= 40.f;
.Lp7_setup:
	v_and_b32_e32 v195, 31, v254
	s_waitcnt vmcnt(0)
	v_and_b32_e32 v0, 63, v254
	s_waitcnt lgkmcnt(0)
	v_lshlrev_b32_e32 v1, 2, v195
	v_lshlrev_b32_e32 v0, 2, v0
	global_load_dword v2, v1, s[74:75] offset:256
	global_load_dword v3, v0, s[74:75]
	global_load_dword v4, v1, s[76:77] offset:256
	global_load_dword v5, v0, s[76:77]
	v_mbcnt_lo_u32_b32 v0, -1, 0
	v_lshlrev_b32_e32 v16, 3, v254
	v_mbcnt_hi_u32_b32 v0, -1, v0
	v_and_b32_e32 v10, 56, v16
	v_and_b32_e32 v201, 64, v0
	v_add_u32_e32 v6, 0x200, v254
	v_xor_b32_e32 v17, 1, v0
	v_lshlrev_b32_e32 v158, 1, v10
	v_add_u32_e32 v10, 64, v201
	v_mul_u32_u24_e32 v8, 0x1556, v254
	v_mov_b32_e32 v9, 12
	s_mov_b32 s4, 0x7060302
	v_mul_u32_u24_e32 v12, 0x1556, v6
	v_cmp_lt_i32_e32 vcc, v17, v10
	v_mul_lo_u16_sdwa v11, v8, v9 dst_sel:DWORD dst_unused:UNUSED_PAD src0_sel:WORD_1 src1_sel:DWORD
	v_perm_b32 v8, v12, v8, s4
	v_mul_lo_u16_sdwa v9, v12, v9 dst_sel:DWORD dst_unused:UNUSED_PAD src0_sel:WORD_1 src1_sel:DWORD
	v_cndmask_b32_e32 v12, v0, v17, vcc
	v_lshlrev_b32_e32 v12, 2, v12
	v_lshrrev_b32_e32 v7, 3, v254
	v_xor_b32_e32 v18, 2, v0
	v_bfe_u32 v1, v254, 5, 1
	s_movk_i32 s6, 0xd0
	v_mul_u32_u24_e32 v13, 0x88, v7
	v_xor_b32_e32 v19, 4, v0
	v_cmp_lt_i32_e32 vcc, v18, v10
	v_lshlrev_b32_e32 v199, 3, v1
	v_mad_u32_u24 v14, v195, s6, 0
	v_lshlrev_b32_e32 v156, 4, v1
	v_mul_i32_i24_e32 v15, 0xffffffb8, v195
	v_xor_b32_e32 v20, 8, v0
	v_add3_u32 v189, 0, v13, v158
	v_cndmask_b32_e32 v13, v0, v18, vcc
	v_cmp_lt_i32_e32 vcc, v19, v10
	v_xor_b32_e32 v21, 16, v0
	v_add_u32_e32 v188, v14, v156
	v_add3_u32 v198, v14, v15, v199
	v_cndmask_b32_e32 v14, v0, v19, vcc
	v_cmp_lt_i32_e32 vcc, v20, v10
	v_xor_b32_e32 v22, 32, v0
	v_sub_u16_e32 v9, v6, v9
	v_cndmask_b32_e32 v15, v0, v20, vcc
	v_cmp_lt_i32_e32 vcc, v21, v10
	v_lshlrev_b32_e32 v190, 4, v9
	v_lshlrev_b32_e32 v9, 2, v15
	v_cndmask_b32_e32 v17, v0, v21, vcc
	v_cmp_lt_i32_e32 vcc, v22, v10
	v_lshlrev_b32_e32 v10, 2, v13
	v_lshlrev_b32_e32 v186, 2, v17
	v_cndmask_b32_e32 v0, v0, v22, vcc
	v_lshlrev_b32_e32 v187, 2, v0
	s_add_u32 s49, s50, 0x4000000
	s_addc_u32 s54, s51, 0
	s_add_u32 s55, s30, 0x6000000
	s_addc_u32 s56, s31, 0
	s_bitcmp1_b32 s2, 4
	s_cbranch_scc1 .Lvt_c1
	s_add_u32 s59, s50, 0x7000000
	s_addc_u32 s60, s51, 0
	s_branch .Lvt_cd
.Lvt_c1:
	s_add_u32 s59, s30, 0x1800000
	s_addc_u32 s60, s31, 0
.Lvt_cd:
	s_mov_b32 s3, 0x42200000
	s_cmpk_lt_i32 s2, 0x200
	s_cselect_b64 s[6:7], -1, 0
	s_and_b32 s42, s2, 3
	s_xor_b32 s43, s42, 7
	s_mov_b32 s5, 0xd00068
	v_pk_mul_lo_u16 v8, v8, s5
	v_mov_b32_e32 v157, 0
	v_sub_u16_e32 v11, v254, v11
	v_lshlrev_b16_e32 v11, 3, v11
	s_movk_i32 s0, 0x100
	v_lshlrev_b32_e32 v192, 1, v11
	v_lshrrev_b32_e32 v191, 16, v8
	v_mov_b32_e32 v159, v157
	v_cmp_gt_u32_e64 s[0:1], s0, v254
	v_lshlrev_b32_e32 v206, 3, v6
	v_lshlrev_b32_e32 v207, 15, v7
	v_add_u32_e32 v196, 0, v191
	v_lshlrev_b32_e32 v194, 2, v1
	s_waitcnt vmcnt(3)
	v_max_f32_e64 v2, |v2|, |v2|
	s_waitcnt vmcnt(2)
	v_max_f32_e64 v3, |v3|, |v3|
	s_waitcnt vmcnt(1)
	v_max_f32_e64 v4, |v4|, |v4|
	s_waitcnt vmcnt(0)
	v_max_f32_e64 v5, |v5|, |v5|
	v_max_f32_e32 v2, v3, v2
	v_max_f32_e32 v3, v5, v4
	ds_bpermute_b32 v4, v12, v2
	ds_bpermute_b32 v5, v12, v3
	v_lshlrev_b32_e32 v12, 2, v14
	s_waitcnt lgkmcnt(1)
	v_max_f32_e32 v4, v4, v4
	s_waitcnt lgkmcnt(0)
	v_max_f32_e32 v5, v5, v5
	v_max_f32_e32 v2, v2, v4
	v_max_f32_e32 v3, v3, v5
	ds_bpermute_b32 v4, v10, v2
	ds_bpermute_b32 v5, v10, v3
	v_and_b32_e32 v10, 0xfff8, v8
	v_lshlrev_b32_e32 v193, 1, v10
	v_add3_u32 v197, 0, v193, v192
	s_waitcnt lgkmcnt(1)
	v_max_f32_e32 v4, v4, v4
	s_waitcnt lgkmcnt(0)
	v_max_f32_e32 v5, v5, v5
	v_max_f32_e32 v2, v2, v4
	v_max_f32_e32 v3, v3, v5
	ds_bpermute_b32 v4, v12, v2
	ds_bpermute_b32 v5, v12, v3
	s_waitcnt lgkmcnt(1)
	v_max_f32_e32 v4, v4, v4
	s_waitcnt lgkmcnt(0)
	v_max_f32_e32 v5, v5, v5
	v_max_f32_e32 v2, v2, v4
	v_max_f32_e32 v3, v3, v5
	ds_bpermute_b32 v4, v9, v2
	ds_bpermute_b32 v5, v9, v3
	s_waitcnt lgkmcnt(1)
	v_max_f32_e32 v0, v4, v4
	s_waitcnt lgkmcnt(0)
	v_max_f32_e32 v4, v5, v5
	v_max_f32_e32 v0, v2, v0
	v_max_f32_e32 v2, v3, v4
	ds_bpermute_b32 v3, v186, v0
	ds_bpermute_b32 v4, v186, v2
	s_waitcnt lgkmcnt(1)
	v_max_f32_e32 v3, v3, v3
	s_waitcnt lgkmcnt(0)
	v_max_f32_e32 v4, v4, v4
	v_max_f32_e32 v0, v0, v3
	v_max_f32_e32 v2, v2, v4
	ds_bpermute_b32 v3, v187, v0
	ds_bpermute_b32 v4, v187, v2
	s_waitcnt lgkmcnt(1)
	v_max_f32_e32 v3, v3, v3
	s_waitcnt lgkmcnt(0)
	v_max_f32_e32 v4, v4, v4
	v_max_f32_e32 v0, v0, v3
	v_max_f32_e32 v2, v2, v4
	v_mul_f32_e32 v0, 0x4166aee6, v0
	v_mul_f32_e32 v0, v2, v0
	v_cmp_ge_f32_e32 vcc, s3, v0
	s_ashr_i32 s3, s2, 2
	s_mul_i32 s58, s3, 0xc0000
	s_mul_hi_i32 s57, s3, 0xc0000
	s_add_u32 s4, s55, s58
	s_addc_u32 s5, s56, s57
	s_ashr_i32 s10, s2, 5
	s_and_b32 s3, s3, 7
	s_ashr_i32 s11, s10, 31
	s_lshl_b64 s[8:9], s[10:11], 13
	v_lshl_add_u64 v[154:155], s[4:5], 0, v[156:157]
	s_lshl_b32 s4, s3, 22
	s_add_u32 s4, s59, s4
	s_addc_u32 s5, s60, 0
	s_add_u32 s4, s4, s8
	s_addc_u32 s5, s5, s9
	s_add_u32 s12, s49, s58
	s_addc_u32 s13, s54, s57
	s_lshl_b32 s48, s10, 12
	s_lshl_b32 s3, s3, 7
	v_lshlrev_b32_e32 v2, 4, v6
	v_mov_b32_e32 v3, v157
	s_add_u32 s10, s50, s3
	v_lshl_add_u64 v[148:149], s[12:13], 0, v[2:3]
	v_lshlrev_b32_e32 v2, 16, v7
	s_addc_u32 s11, s51, 0
	v_lshlrev_b32_e32 v156, 4, v254
	v_lshl_add_u64 v[2:3], s[4:5], 0, v[2:3]
	s_cmpk_lg_i32 s86, 0x100
	v_lshl_add_u64 v[152:153], s[12:13], 0, v[156:157]
	v_lshl_add_u64 v[150:151], v[2:3], 0, v[158:159]
	s_cselect_b64 s[12:13], -1, 0
	s_mov_b64 s[4:5], 0
	s_cmp_eq_u32 s98, 1
	s_cbranch_scc0 .Lp7_attn
	s_mov_b64 s[0:1], exec
	s_branch .Lp7_h3

; #define ATT_LOADG(t) do { kA = *(const u32x4*)(Kh + (size_t)(t) * 6144 + tid * 8); if (tid < 256) kB = *(const u32x4*)(Kh + (size_t)(t) * 6144 + c2 * 8); \
;         vA = *(const u32x4*)(Vh + (size_t)vr * T + 64 * (t) + vc * 8); } while (0)
; #define ATT_STORE(buf) do { *(LAS u32x4*)(Kb + (buf) * 6656 + kr1 * 104 + kc1 * 8) = kA; if (tid < 256) *(LAS u32x4*)(Kb + (buf) * 6656 + kr2 * 104 + kc2 * 8) = kB; \
;         *(LAS u32x2*)(Vb + (buf) * 4352 + vr * 68 + vc * 8) = (u32x2){vA[0], vA[1]}; *(LAS u32x2*)(Vb + (buf) * 4352 + vr * 68 + vc * 8 + 4) = (u32x2){vA[2], vA[3]}; } while (0)
; #define ATT_LOADG(t) do { kA = *(const u32x4*)(Kh + (size_t)(t) * 6144 + tid * 8); if (tid < 256) kB = *(const u32x4*)(Kh + (size_t)(t) * 6144 + c2 * 8); \
;         vA = *(const u32x4*)(Vh + (size_t)vr * T + 64 * (t) + vc * 8); } while (0)
; #define ATT_STORE(buf) do { *(LAS u32x4*)(Kb + (buf) * 6656 + kr1 * 104 + kc1 * 8) = kA; if (tid < 256) *(LAS u32x4*)(Kb + (buf) * 6656 + kr2 * 104 + kc2 * 8) = kB; \
;         *(LAS u32x2*)(Vb + (buf) * 4352 + vr * 68 + vc * 8) = (u32x2){vA[0], vA[1]}; *(LAS u32x2*)(Vb + (buf) * 4352 + vr * 68 + vc * 8 + 4) = (u32x2){vA[2], vA[3]}; } while (0)
; __device__ __forceinline__ void attn_unit64(const bf16_t* Q, const bf16_t* K, const bf16_t* Vt, bf16_t* O, int bh, int qb8, float mfix, LAS unsigned char* lds) {
;     ...
;     for (int d0 = 0; d0 < 6; ++d0) { Qs[512 * d0] = __builtin_nontemporal_load((const bf16x8*)(Qh + (size_t)(qw + r) * 96 + 16 * d0 + 8 * hh)); Qs[512 * (6 + d0)] = __builtin_nontemporal_load((const bf16x8*)(Qh + (size_t)(qw + 32 + r) * 96 + 16 * d0 + 8 * hh)); }
;     f32x16 oA0, oA1, oB0, oB1;
; #pragma unroll
;     for (int i = 0; i < 16; ++i) { oA0[i] = 0.f; oA1[i] = 0.f; oB0[i] = 0.f; oB1[i] = 0.f; }
;     float lA = 0.f, lB = 0.f;
;     const int c2 = 512 + tid, kr1 = tid / 12, kc1 = tid % 12, kr2 = c2 / 12, kc2 = c2 % 12, vr = tid >> 3, vc = tid & 7;
;     u32x4 kA, kB = {0u, 0u, 0u, 0u}, vA;
;     ...
;     ATT_LOADG(0); ATT_STORE(0); __syncthreads();
.LBB0_790:
	s_or_b64 exec, exec, s[4:5]
	global_load_dwordx4 v[120:123], v[150:151], off
	s_waitcnt vmcnt(1)
	ds_write_b128 v197, v[112:115]
	s_and_saveexec_b64 s[4:5], s[0:1]
	v_add_u32_e32 v16, v196, v190
	ds_write_b128 v16, v[116:119]
	s_or_b64 exec, exec, s[4:5]
	s_lshl_b32 s25, s43, 3
	s_lshr_b32 s24, s16, 6
	s_add_i32 s24, s24, s25
	s_add_i32 s25, s25, 8
	s_add_u32 s4, s50, s58
	v_add_u32_e32 v16, 0x6800, v189
	v_mov_b32_e32 v157, 0
	s_addc_u32 s5, s51, s57
	s_waitcnt vmcnt(0)
	ds_write2_b64 v16, v[120:121], v[122:123] offset1:1
	v_lshl_add_u64 v[16:17], s[4:5], 0, v[156:157]
	s_mov_b64 s[4:5], 0x4003000
	v_lshl_add_u64 v[124:125], v[16:17], 0, s[4:5]
	s_lshl_b32 s4, s2, 20
	s_and_b32 s4, s4, 0x1c00000
	v_lshlrev_b32_e32 v16, 13, v254
	s_add_u32 s4, s8, s4
	v_and_b32_e32 v156, 0x7f0000, v16
	s_addc_u32 s5, s9, 0
	v_and_b32_e32 v18, 7, v254
	v_lshl_add_u64 v[16:17], s[4:5], 0, v[156:157]
	v_lshlrev_b32_e32 v156, 4, v18
	v_lshl_add_u64 v[16:17], v[16:17], 0, v[156:157]
	s_add_u32 s4, s59, 0x80
	s_addc_u32 s5, s60, 0
	v_mov_b32_e32 v64, v157
	v_mov_b32_e32 v65, v157
	v_lshl_add_u64 v[126:127], v[16:17], 0, s[4:5]
	v_mov_b32_e32 v66, v157
	v_mov_b32_e32 v67, v157
	v_mov_b32_e32 v68, v157
	v_mov_b32_e32 v69, v157
	v_mov_b32_e32 v70, v157
	v_mov_b32_e32 v71, v157
	v_mov_b32_e32 v72, v157
	v_mov_b32_e32 v73, v157
	v_mov_b32_e32 v74, v157
	v_mov_b32_e32 v75, v157
	v_mov_b32_e32 v76, v157
	v_mov_b32_e32 v77, v157
	v_mov_b32_e32 v78, v157
	v_mov_b32_e32 v79, v157
	v_mov_b64_e32 v[48:49], v[64:65]
	v_mov_b64_e32 v[32:33], v[64:65]
	v_mov_b64_e32 v[16:17], v[64:65]
	s_addk_i32 s26, 0x200
	s_mov_b32 s27, 0
	v_mov_b32_e32 v156, v157
	s_mov_b64 s[16:17], 0x3000
	s_mov_b64 s[18:19], 0x80
	v_mov_b32_e32 v176, 0xf149f2ca
	v_mov_b64_e32 v[128:129], v[126:127]
	v_mov_b64_e32 v[130:131], v[124:125]
	v_mov_b64_e32 v[50:51], v[66:67]
	v_mov_b64_e32 v[52:53], v[68:69]
	v_mov_b64_e32 v[54:55], v[70:71]
	v_mov_b64_e32 v[56:57], v[72:73]
	v_mov_b64_e32 v[58:59], v[74:75]
	v_mov_b64_e32 v[60:61], v[76:77]
	v_mov_b64_e32 v[62:63], v[78:79]
	v_mov_b64_e32 v[34:35], v[66:67]
	v_mov_b64_e32 v[36:37], v[68:69]
	v_mov_b64_e32 v[38:39], v[70:71]
	v_mov_b64_e32 v[40:41], v[72:73]
	v_mov_b64_e32 v[42:43], v[74:75]
	v_mov_b64_e32 v[44:45], v[76:77]
	v_mov_b64_e32 v[46:47], v[78:79]
	v_mov_b64_e32 v[18:19], v[66:67]
	v_mov_b64_e32 v[20:21], v[68:69]
	v_mov_b64_e32 v[22:23], v[70:71]
	v_mov_b64_e32 v[24:25], v[72:73]
	v_mov_b64_e32 v[26:27], v[74:75]
	v_mov_b64_e32 v[28:29], v[76:77]
	v_mov_b64_e32 v[30:31], v[78:79]
	s_mov_b32 s33, 0
	s_waitcnt lgkmcnt(0)
	s_barrier
	ds_read_b128 v[132:135], v200 offset:44032
	ds_read_b128 v[136:139], v200 offset:52224
	ds_read_b128 v[140:143], v200 offset:60416
	ds_read_b128 v[144:147], v201 offset:24576
	ds_read_b128 v[206:209], v201 offset:32768
	ds_read_b128 v[210:213], v201 offset:40960
	ds_read_b128 v[214:217], v201 offset:49152
	ds_read_b128 v[218:221], v201 offset:57344
	ds_read_b128 v[232:235], v202
	ds_read_b128 v[236:239], v203
	ds_read_b128 v[240:243], v204
	ds_read_b128 v[244:247], v205
	s_waitcnt lgkmcnt(0)
